# grid syncs 2..16 replaced by two-level atomic counter barrier in d_ws (device memory) instead of cooperative-groups sync struct
# speedup vs baseline: 1.0235x; 1.0235x over previous
_Z8yoco_fwd4Args:
	s_load_dwordx16 s[48:63], s[0:1], 0x0
	s_load_dwordx16 s[76:91], s[0:1], 0x40
	s_load_dwordx8 s[92:99], s[0:1], 0x80
	s_load_dword s3, s[0:1], 0xa0
	s_add_u32 s4, s0, 0xa0
	s_addc_u32 s5, s1, 0
	v_and_b32_e32 v1, 0x3ff, v0
	v_writelane_b32 v255, s4, 0
	v_readfirstlane_b32 s36, v1
	s_lshr_b32 s0, s36, 6
	v_writelane_b32 v255, s5, 1
	s_lshl_b32 s74, s2, 3
	v_writelane_b32 v255, s0, 2
	s_add_i32 s0, s0, s74
	s_waitcnt lgkmcnt(0)
	v_writelane_b32 v255, s2, 63
	v_writelane_b32 v255, s3, 62
	v_writelane_b32 v255, s96, 60
	v_writelane_b32 v255, s97, 61
	s_cmp_lg_u32 s2, 0
	s_cbranch_scc1 .Lgb_init_done
	v_mbcnt_lo_u32_b32 v2, -1, 0
	v_mbcnt_hi_u32_b32 v2, -1, v2
	v_lshlrev_b32_e32 v2, 8, v2
	v_mov_b32_e32 v3, 0
	s_add_u32 s4, s96, 0x7e00000
	s_addc_u32 s5, s97, 0
	global_atomic_swap v2, v3, s[4:5]
	s_waitcnt vmcnt(0)
.Lgb_init_done:
	s_lshl_b32 s46, s3, 3
	v_writelane_b32 v255, s0, 3
	s_cmp_lt_i32 s98, 1
	s_nop 0
	v_writelane_b32 v255, s1, 4
	s_cselect_b64 s[0:1], -1, 0
	s_cmp_gt_i32 s99, 0
	s_cselect_b64 s[4:5], -1, 0
	s_and_b64 s[0:1], s[0:1], s[4:5]
	s_andn2_b64 vcc, exec, s[0:1]
	s_cbranch_vccnz .LBB0_210
	s_abs_i32 s13, s46
	v_cvt_f32_u32_e32 v2, s13
	v_readlane_b32 s0, v255, 2
	s_lshl_b32 s0, s0, 14
	s_add_i32 s12, s0, 0
	v_rcp_iflag_f32_e32 v2, v2
	v_readlane_b32 s0, v255, 3
	v_readlane_b32 s1, v255, 4
	s_sub_i32 s1, 0, s13
	v_mul_f32_e32 v2, 0x4f7ffffe, v2
	v_cvt_u32_f32_e32 v2, v2
	s_mov_b32 s4, s0
	s_ashr_i32 s5, s0, 31
	s_abs_i32 s0, s0
	v_readfirstlane_b32 s14, v2
	s_mul_i32 s1, s1, s14
	s_mul_hi_u32 s1, s14, s1
	s_add_i32 s14, s14, s1
	s_mul_hi_u32 s1, s0, s14
	s_mul_i32 s1, s1, s13
	s_sub_i32 s0, s0, s1
	s_sub_i32 s1, s0, s13
	s_cmp_ge_u32 s0, s13
	s_cselect_b32 s0, s1, s0
	s_sub_i32 s1, s0, s13
	s_cmp_ge_u32 s0, s13
	s_cselect_b32 s0, s1, s0
	s_xor_b32 s0, s0, s5
	v_writelane_b32 v255, s4, 3
	s_sub_i32 s0, s0, s5
	s_ashr_i32 s1, s0, 31
	s_and_b32 s1, s1, s46
	s_add_i32 s10, s1, s0
	v_writelane_b32 v255, s5, 4
	s_cmpk_lt_i32 s10, 0xc40
	s_cbranch_scc0 .LBB0_36
	v_mbcnt_lo_u32_b32 v2, -1, 0
	v_mbcnt_hi_u32_b32 v6, -1, v2
	v_and_b32_e32 v2, 31, v6
	v_lshlrev_b32_e32 v4, 2, v2
	v_mov_b32_e32 v5, 0
	v_lshrrev_b32_e32 v8, 5, v6
	v_lshl_add_u64 v[2:3], s[52:53], 0, v[4:5]
	v_add_u32_e32 v7, s12, v4
	s_movk_i32 s4, 0x84
	v_mov_b32_e32 v4, 0x210
	v_mad_u32_u24 v12, v8, s4, v4
	v_mov_b32_e32 v4, 0x420
	v_mad_u32_u24 v14, v8, s4, v4
	v_mov_b32_e32 v4, 0x630
	v_mad_u32_u24 v13, v8, s4, v4
	v_mov_b32_e32 v4, 0x840
	v_mad_u32_u24 v15, v8, s4, v4
	v_lshlrev_b32_e32 v4, 3, v6
	s_cmp_lg_u64 s[50:51], 0
	v_lshrrev_b32_e32 v9, 3, v6
	v_and_b32_e32 v4, 56, v4
	s_cselect_b64 s[0:1], -1, 0
	v_mul_u32_u24_e32 v6, 0x84, v4
	v_lshlrev_b32_e32 v10, 2, v9
	v_mul_u32_u24_e32 v11, 0x84, v8
	v_lshlrev_b32_e32 v4, 1, v4
	v_add3_u32 v10, s12, v6, v10
	v_cndmask_b32_e64 v6, 0, 1, s[0:1]
	v_lshl_add_u64 v[4:5], s[96:97], 0, v[4:5]
	s_lshl_b32 s11, s10, 5
	s_lshl_b32 s15, s46, 5
	s_movk_i32 s16, 0x3100
	v_add_u32_e32 v11, v7, v11
	v_add_u32_e32 v12, v7, v12
	v_add_u32_e32 v13, v7, v13
	v_cmp_ne_u32_e64 s[0:1], 1, v6
	v_add_u32_e32 v14, v7, v14
	v_add_u32_e32 v15, v7, v15
	s_branch .LBB0_4

.LBB0_227:
	s_cmp_lt_i32 s99, 3
	s_cbranch_scc1 .LBB0_239
	v_lshrrev_b32_e32 v2, 20, v0
	v_lshrrev_b32_e32 v3, 10, v0
	v_or_b32_e32 v2, v3, v2
	s_movk_i32 s0, 0x3ff
	v_and_or_b32 v2, v2, s0, v1
	v_cmp_eq_u32_e32 vcc, 0, v2
	s_waitcnt vmcnt(0)
	s_barrier
	s_and_saveexec_b64 s[0:1], vcc
	s_cbranch_execz .LBB0_238
	buffer_wbl2 sc1
	s_waitcnt vmcnt(0)
	v_readlane_b32 s6, v255, 60
	v_readlane_b32 s7, v255, 61
	v_readlane_b32 s8, v255, 63
	v_readlane_b32 s9, v255, 62
	s_add_u32 s6, s6, 0x7e00000
	s_addc_u32 s7, s7, 0
	s_and_b32 s10, s8, 7
	s_sub_i32 s11, s9, s10
	s_add_i32 s11, s11, 7
	s_lshr_b32 s11, s11, 3
	s_sub_i32 s11, 0x10001, s11
	s_cmp_lt_u32 s8, 8
	s_cselect_b32 s11, s11, 1
	s_lshl_b32 s8, s10, 8
	s_add_i32 s8, s8, 0x100
	v_mov_b32_e32 v2, s8
	v_mov_b32_e32 v3, s11
	global_atomic_add v3, v2, v3, s[6:7] sc0
	s_min_u32 s9, s9, 8
	s_sub_i32 s9, 0x10001, s9
	s_cmp_eq_u32 s10, 0
	s_cselect_b32 s9, s9, 1
	v_mov_b32_e32 v2, 0
	s_waitcnt vmcnt(0)
	v_readfirstlane_b32 s8, v3
	s_add_i32 s10, s8, s11
	s_xor_b32 s10, s10, s8
	s_lshr_b32 s10, s10, 16
	s_lshr_b32 s8, s8, 16
	s_cmp_eq_u32 s10, 0
	s_cbranch_scc1 .Lgb_poll_1
	v_mov_b32_e32 v3, s9
	global_atomic_add v2, v3, s[6:7]
.Lgb_poll_1:
	s_mov_b32 s10, 0
.Lgb_spin_1:
	global_load_dword v3, v2, s[6:7] sc1
	s_waitcnt vmcnt(0)
	v_readfirstlane_b32 s11, v3
	s_lshr_b32 s11, s11, 16
	s_cmp_lg_u32 s11, s8
	s_cbranch_scc1 .Lgb_done_1
	s_sleep 1
	s_add_i32 s10, s10, 1
	s_cmp_lt_u32 s10, 0x8000
	s_cbranch_scc1 .Lgb_spin_1
.Lgb_done_1:
	buffer_inv sc1
	s_waitcnt vmcnt(0)

.LBB0_260:
	v_readlane_b32 s48, v255, 5
	s_cmp_gt_i32 s99, 3
	v_readlane_b32 s62, v255, 19
	v_readlane_b32 s63, v255, 20
	v_readlane_b32 s49, v255, 6
	v_readlane_b32 s50, v255, 7
	v_readlane_b32 s51, v255, 8
	v_readlane_b32 s52, v255, 9
	v_readlane_b32 s53, v255, 10
	v_readlane_b32 s54, v255, 11
	v_readlane_b32 s55, v255, 12
	v_readlane_b32 s56, v255, 13
	v_readlane_b32 s57, v255, 14
	v_readlane_b32 s58, v255, 15
	v_readlane_b32 s59, v255, 16
	v_readlane_b32 s60, v255, 17
	v_readlane_b32 s61, v255, 18
	s_cbranch_scc0 .LBB0_272
	v_lshrrev_b32_e32 v2, 20, v0
	v_lshrrev_b32_e32 v3, 10, v0
	v_or_b32_e32 v2, v3, v2
	s_movk_i32 s0, 0x3ff
	v_and_or_b32 v2, v2, s0, v1
	v_cmp_eq_u32_e32 vcc, 0, v2
	s_waitcnt vmcnt(0)
	s_barrier
	s_and_saveexec_b64 s[0:1], vcc
	s_cbranch_execz .LBB0_271
	buffer_wbl2 sc1
	s_waitcnt vmcnt(0)
	v_readlane_b32 s6, v255, 60
	v_readlane_b32 s7, v255, 61
	v_readlane_b32 s8, v255, 63
	v_readlane_b32 s9, v255, 62
	s_add_u32 s6, s6, 0x7e00000
	s_addc_u32 s7, s7, 0
	s_and_b32 s10, s8, 7
	s_sub_i32 s11, s9, s10
	s_add_i32 s11, s11, 7
	s_lshr_b32 s11, s11, 3
	s_sub_i32 s11, 0x10001, s11
	s_cmp_lt_u32 s8, 8
	s_cselect_b32 s11, s11, 1
	s_lshl_b32 s8, s10, 8
	s_add_i32 s8, s8, 0x100
	v_mov_b32_e32 v2, s8
	v_mov_b32_e32 v3, s11
	global_atomic_add v3, v2, v3, s[6:7] sc0
	s_min_u32 s9, s9, 8
	s_sub_i32 s9, 0x10001, s9
	s_cmp_eq_u32 s10, 0
	s_cselect_b32 s9, s9, 1
	v_mov_b32_e32 v2, 0
	s_waitcnt vmcnt(0)
	v_readfirstlane_b32 s8, v3
	s_add_i32 s10, s8, s11
	s_xor_b32 s10, s10, s8
	s_lshr_b32 s10, s10, 16
	s_lshr_b32 s8, s8, 16
	s_cmp_eq_u32 s10, 0
	s_cbranch_scc1 .Lgb_poll_2
	v_mov_b32_e32 v3, s9
	global_atomic_add v2, v3, s[6:7]

.LBB0_276:
	s_cmp_lt_u32 s99, 5
	s_cbranch_scc1 .LBB0_288
	v_lshrrev_b32_e32 v2, 20, v0
	v_lshrrev_b32_e32 v3, 10, v0
	v_or_b32_e32 v2, v3, v2
	s_movk_i32 s0, 0x3ff
	v_and_or_b32 v2, v2, s0, v1
	v_cmp_eq_u32_e32 vcc, 0, v2
	s_waitcnt vmcnt(0)
	s_barrier
	s_and_saveexec_b64 s[0:1], vcc
	s_cbranch_execz .LBB0_287
	buffer_wbl2 sc1
	s_waitcnt vmcnt(0)
	v_readlane_b32 s6, v255, 60
	v_readlane_b32 s7, v255, 61
	v_readlane_b32 s8, v255, 63
	v_readlane_b32 s9, v255, 62
	s_add_u32 s6, s6, 0x7e00000
	s_addc_u32 s7, s7, 0
	s_and_b32 s10, s8, 7
	s_sub_i32 s11, s9, s10
	s_add_i32 s11, s11, 7
	s_lshr_b32 s11, s11, 3
	s_sub_i32 s11, 0x10001, s11
	s_cmp_lt_u32 s8, 8
	s_cselect_b32 s11, s11, 1
	s_lshl_b32 s8, s10, 8
	s_add_i32 s8, s8, 0x100
	v_mov_b32_e32 v2, s8
	v_mov_b32_e32 v3, s11
	global_atomic_add v3, v2, v3, s[6:7] sc0
	s_min_u32 s9, s9, 8
	s_sub_i32 s9, 0x10001, s9
	s_cmp_eq_u32 s10, 0
	s_cselect_b32 s9, s9, 1
	v_mov_b32_e32 v2, 0
	s_waitcnt vmcnt(0)
	v_readfirstlane_b32 s8, v3
	s_add_i32 s10, s8, s11
	s_xor_b32 s10, s10, s8
	s_lshr_b32 s10, s10, 16
	s_lshr_b32 s8, s8, 16
	s_cmp_eq_u32 s10, 0
	s_cbranch_scc1 .Lgb_poll_3
	v_mov_b32_e32 v3, s9
	global_atomic_add v2, v3, s[6:7]

.LBB0_324:
	s_cmp_lt_i32 s99, 6
	s_cbranch_scc1 .LBB0_336
	v_lshrrev_b32_e32 v2, 20, v0
	v_lshrrev_b32_e32 v3, 10, v0
	v_or_b32_e32 v2, v3, v2
	s_movk_i32 s0, 0x3ff
	v_and_or_b32 v2, v2, s0, v1
	v_cmp_eq_u32_e32 vcc, 0, v2
	s_waitcnt vmcnt(0)
	s_barrier
	s_and_saveexec_b64 s[0:1], vcc
	s_cbranch_execz .LBB0_335
	buffer_wbl2 sc1
	s_waitcnt vmcnt(0)
	v_readlane_b32 s6, v255, 60
	v_readlane_b32 s7, v255, 61
	v_readlane_b32 s8, v255, 63
	v_readlane_b32 s9, v255, 62
	s_add_u32 s6, s6, 0x7e00000
	s_addc_u32 s7, s7, 0
	s_and_b32 s10, s8, 7
	s_sub_i32 s11, s9, s10
	s_add_i32 s11, s11, 7
	s_lshr_b32 s11, s11, 3
	s_sub_i32 s11, 0x10001, s11
	s_cmp_lt_u32 s8, 8
	s_cselect_b32 s11, s11, 1
	s_lshl_b32 s8, s10, 8
	s_add_i32 s8, s8, 0x100
	v_mov_b32_e32 v2, s8
	v_mov_b32_e32 v3, s11
	global_atomic_add v3, v2, v3, s[6:7] sc0
	s_min_u32 s9, s9, 8
	s_sub_i32 s9, 0x10001, s9
	s_cmp_eq_u32 s10, 0
	s_cselect_b32 s9, s9, 1
	v_mov_b32_e32 v2, 0
	s_waitcnt vmcnt(0)
	v_readfirstlane_b32 s8, v3
	s_add_i32 s10, s8, s11
	s_xor_b32 s10, s10, s8
	s_lshr_b32 s10, s10, 16
	s_lshr_b32 s8, s8, 16
	s_cmp_eq_u32 s10, 0
	s_cbranch_scc1 .Lgb_poll_4
	v_mov_b32_e32 v3, s9
	global_atomic_add v2, v3, s[6:7]

.LBB0_357:
	s_cmp_lt_i32 s99, 7
	s_cbranch_scc1 .LBB0_369
	v_lshrrev_b32_e32 v2, 20, v0
	v_lshrrev_b32_e32 v3, 10, v0
	v_or_b32_e32 v2, v3, v2
	s_movk_i32 s0, 0x3ff
	v_and_or_b32 v2, v2, s0, v1
	v_cmp_eq_u32_e32 vcc, 0, v2
	s_waitcnt vmcnt(0)
	s_barrier
	s_and_saveexec_b64 s[0:1], vcc
	s_cbranch_execz .LBB0_368
	buffer_wbl2 sc1
	s_waitcnt vmcnt(0)
	v_readlane_b32 s6, v255, 60
	v_readlane_b32 s7, v255, 61
	v_readlane_b32 s8, v255, 63
	v_readlane_b32 s9, v255, 62
	s_add_u32 s6, s6, 0x7e00000
	s_addc_u32 s7, s7, 0
	s_and_b32 s10, s8, 7
	s_sub_i32 s11, s9, s10
	s_add_i32 s11, s11, 7
	s_lshr_b32 s11, s11, 3
	s_sub_i32 s11, 0x10001, s11
	s_cmp_lt_u32 s8, 8
	s_cselect_b32 s11, s11, 1
	s_lshl_b32 s8, s10, 8
	s_add_i32 s8, s8, 0x100
	v_mov_b32_e32 v2, s8
	v_mov_b32_e32 v3, s11
	global_atomic_add v3, v2, v3, s[6:7] sc0
	s_min_u32 s9, s9, 8
	s_sub_i32 s9, 0x10001, s9
	s_cmp_eq_u32 s10, 0
	s_cselect_b32 s9, s9, 1
	v_mov_b32_e32 v2, 0
	s_waitcnt vmcnt(0)
	v_readfirstlane_b32 s8, v3
	s_add_i32 s10, s8, s11
	s_xor_b32 s10, s10, s8
	s_lshr_b32 s10, s10, 16
	s_lshr_b32 s8, s8, 16
	s_cmp_eq_u32 s10, 0
	s_cbranch_scc1 .Lgb_poll_5
	v_mov_b32_e32 v3, s9
	global_atomic_add v2, v3, s[6:7]

.LBB0_379:
	s_cmp_lt_u32 s99, 8
	s_cbranch_scc1 .LBB0_391
	v_lshrrev_b32_e32 v2, 20, v0
	v_lshrrev_b32_e32 v3, 10, v0
	v_or_b32_e32 v2, v3, v2
	s_movk_i32 s0, 0x3ff
	v_and_or_b32 v2, v2, s0, v1
	v_cmp_eq_u32_e32 vcc, 0, v2
	s_waitcnt vmcnt(0)
	s_barrier
	s_and_saveexec_b64 s[0:1], vcc
	s_cbranch_execz .LBB0_390
	buffer_wbl2 sc1
	s_waitcnt vmcnt(0)
	v_readlane_b32 s6, v255, 60
	v_readlane_b32 s7, v255, 61
	v_readlane_b32 s8, v255, 63
	v_readlane_b32 s9, v255, 62
	s_add_u32 s6, s6, 0x7e00000
	s_addc_u32 s7, s7, 0
	s_and_b32 s10, s8, 7
	s_sub_i32 s11, s9, s10
	s_add_i32 s11, s11, 7
	s_lshr_b32 s11, s11, 3
	s_sub_i32 s11, 0x10001, s11
	s_cmp_lt_u32 s8, 8
	s_cselect_b32 s11, s11, 1
	s_lshl_b32 s8, s10, 8
	s_add_i32 s8, s8, 0x100
	v_mov_b32_e32 v2, s8
	v_mov_b32_e32 v3, s11
	global_atomic_add v3, v2, v3, s[6:7] sc0
	s_min_u32 s9, s9, 8
	s_sub_i32 s9, 0x10001, s9
	s_cmp_eq_u32 s10, 0
	s_cselect_b32 s9, s9, 1
	v_mov_b32_e32 v2, 0
	s_waitcnt vmcnt(0)
	v_readfirstlane_b32 s8, v3
	s_add_i32 s10, s8, s11
	s_xor_b32 s10, s10, s8
	s_lshr_b32 s10, s10, 16
	s_lshr_b32 s8, s8, 16
	s_cmp_eq_u32 s10, 0
	s_cbranch_scc1 .Lgb_poll_6
	v_mov_b32_e32 v3, s9
	global_atomic_add v2, v3, s[6:7]

.LBB0_391:
	s_add_u32 s67, s96, 0x9000000
	s_addc_u32 s70, s97, 0
	s_add_u32 s0, s96, 0x1d00000
	s_addc_u32 s82, s97, 0
	s_cmpk_lt_i32 s2, 0xa00
	s_cselect_b64 s[14:15], -1, 0
	s_ashr_i32 s47, s2, 31
	v_writelane_b32 v255, s0, 5
	s_lshr_b32 s0, s47, 29
	s_add_i32 s0, s2, s0
	s_ashr_i32 s7, s0, 3
	s_and_b32 s0, s0, -8
	s_sub_i32 s8, s2, s0
	s_cmp_gt_i32 s8, -1
	s_cselect_b64 s[0:1], -1, 0
	v_writelane_b32 v255, s0, 47
	s_ashr_i32 s49, s3, 31
	s_and_b32 s5, s3, 7
	v_writelane_b32 v255, s1, 48
	s_and_b32 s1, s74, 56
	v_readlane_b32 s4, v255, 2
	s_lshl_b32 s0, s4, 14
	s_add_i32 s71, s0, 0
	s_lshr_b32 s0, s3, 3
	s_mul_i32 s0, s1, s0
	s_add_i32 s0, s0, s2
	s_and_b32 s0, s0, -8
	s_add_i32 s6, s0, s4
	s_add_u32 s26, s96, 0x11000000
	s_addc_u32 s27, s97, 0
	s_add_u32 s24, s96, 0x2b000000
	s_addc_u32 s25, s97, 0
	s_add_u32 s20, s96, 0x7800000
	s_addc_u32 s21, s97, 0
	s_add_u32 s28, s96, 0x23000000
	s_addc_u32 s29, s97, 0
	s_add_u32 s40, s96, 0x31000000
	s_addc_u32 s41, s97, 0
	v_readlane_b32 s0, v255, 3
	s_cmp_lt_i32 s0, 0x8000
	s_cselect_b64 s[22:23], -1, 0
	s_cmp_lt_i32 s8, 0
	s_movk_i32 s34, 0x141
	s_cselect_b32 s4, s34, 0x140
	s_mul_i32 s4, s8, s4
	v_readlane_b32 s1, v255, 4
	v_writelane_b32 v255, s8, 49
	s_add_i32 s4, s4, s7
	v_writelane_b32 v255, s7, 50
	s_mul_hi_i32 s7, s4, 0x66666667
	s_lshr_b32 s8, s7, 31
	s_ashr_i32 s7, s7, 5
	s_add_i32 s7, s7, s8
	s_lshl_b32 s8, s7, 2
	s_mulk_i32 s7, 0x50
	s_sub_i32 s7, s4, s7
	s_bfe_i32 s4, s7, 0x80000
	s_bfe_u32 s4, s4, 0x2000d
	s_add_i32 s9, s7, s4
	s_bfe_i32 s4, s9, 0x80000
	s_and_b32 s9, s9, 0xfc
	s_sub_i32 s7, s7, s9
	s_sext_i32_i16 s10, s4
	s_sext_i32_i8 s7, s7
	s_lshr_b32 s4, s10, 2
	s_add_i32 s8, s8, s7
	s_ashr_i32 s77, s10, 2
	s_mov_b32 s12, s0
	s_cmp_eq_u32 s5, 0
	s_cselect_b32 s66, s6, s12
	s_cmpk_lt_i32 s66, 0x3000
	s_mov_b32 s6, s8
	s_cselect_b64 s[12:13], -1, 0
	s_ashr_i32 s9, s8, 31
	v_writelane_b32 v255, s6, 43
	s_bfe_i64 s[4:5], s[4:5], 0x100000
	s_lshl_b64 s[4:5], s[4:5], 20
	v_writelane_b32 v255, s7, 44
	s_lshl_b64 s[6:7], s[8:9], 20
	s_add_u32 s42, s67, s6
	v_writelane_b32 v255, s4, 51
	s_addc_u32 s43, s70, s7
	v_lshrrev_b32_e32 v2, 20, v0
	v_writelane_b32 v255, s5, 52
	s_add_u32 s4, s42, 0x80000
	s_addc_u32 s5, s43, 0
	v_writelane_b32 v255, s4, 53
	v_lshrrev_b32_e32 v0, 10, v0
	v_or_b32_e32 v0, v0, v2
	v_writelane_b32 v255, s5, 54
	v_writelane_b32 v255, s20, 45
	s_movk_i32 s0, 0x3ff
	v_and_or_b32 v0, v0, s0, v1
	v_writelane_b32 v255, s21, 46
	v_writelane_b32 v255, s22, 39
	v_cmp_eq_u32_e64 s[0:1], 0, v0
	v_mbcnt_hi_u32_b32 v252, -1, v147
	v_writelane_b32 v255, s23, 40
	v_ashrrev_i32_e32 v0, 1, v252
	v_writelane_b32 v255, s0, 41
	v_and_b32_e32 v253, 15, v252
	v_and_b32_e32 v199, -8, v0
	v_and_b32_e32 v0, 48, v252
	v_writelane_b32 v255, s1, 42
	v_lshlrev_b32_e32 v2, 4, v252
	v_lshl_or_b32 v254, v253, 6, v0
	v_lshlrev_b32_e32 v0, 2, v252
	v_writelane_b32 v255, s12, 37
	s_mov_b32 s73, 0
	s_lshl_b32 s35, s3, 4
	v_mov_b32_e32 v1, 0
	s_mov_b64 s[44:45], 0x80
	s_movk_i32 s80, 0x80
	s_mov_b32 s48, 0x3e0293ee
	s_mov_b32 s81, 1.0
	v_mov_b32_e32 v196, 0x358637bd
	s_movk_i32 s83, 0x2400
	v_mov_b32_e32 v198, 1
	v_and_b32_e32 v200, 0xfffffc00, v2
	v_and_b32_e32 v197, 32, v0
	v_mov_b64_e32 v[178:179], 0x9ff
	v_mov_b32_e32 v201, 0x42800000
	v_mov_b32_e32 v202, 0xff800000
	s_mov_b32 s84, 0
	v_writelane_b32 v255, s13, 38
	s_branch .LBB0_395
.LBB0_393:
	s_or_b64 exec, exec, s[4:5]
	s_barrier

.LBB0_492:
	s_add_i32 s16, s85, 8
	s_cmp_ge_i32 s16, s99
	s_cbranch_scc1 .LBB0_504
	s_waitcnt vmcnt(0) lgkmcnt(0)
	s_barrier
	s_and_saveexec_b64 s[4:5], s[0:1]
	s_cbranch_execz .LBB0_503
	buffer_wbl2 sc1
	s_waitcnt vmcnt(0)
	v_readlane_b32 s6, v255, 60
	v_readlane_b32 s7, v255, 61
	v_readlane_b32 s8, v255, 63
	v_readlane_b32 s9, v255, 62
	s_add_u32 s6, s6, 0x7e00000
	s_addc_u32 s7, s7, 0
	s_and_b32 s10, s8, 7
	s_sub_i32 s11, s9, s10
	s_add_i32 s11, s11, 7
	s_lshr_b32 s11, s11, 3
	s_sub_i32 s11, 0x10001, s11
	s_cmp_lt_u32 s8, 8
	s_cselect_b32 s11, s11, 1
	s_lshl_b32 s8, s10, 8
	s_add_i32 s8, s8, 0x100
	v_mov_b32_e32 v2, s8
	v_mov_b32_e32 v3, s11
	global_atomic_add v3, v2, v3, s[6:7] sc0
	s_min_u32 s9, s9, 8
	s_sub_i32 s9, 0x10001, s9
	s_cmp_eq_u32 s10, 0
	s_cselect_b32 s9, s9, 1
	v_mov_b32_e32 v2, 0
	s_waitcnt vmcnt(0)
	v_readfirstlane_b32 s8, v3
	s_add_i32 s10, s8, s11
	s_xor_b32 s10, s10, s8
	s_lshr_b32 s10, s10, 16
	s_lshr_b32 s8, s8, 16
	s_cmp_eq_u32 s10, 0
	s_cbranch_scc1 .Lgb_poll_7
	v_mov_b32_e32 v3, s9
	global_atomic_add v2, v3, s[6:7]

.LBB0_523:
	s_add_i32 s16, s85, 9
	s_cmp_lt_i32 s16, s99
	s_cbranch_scc0 .LBB0_535
	s_waitcnt vmcnt(0) lgkmcnt(0)
	s_barrier
	s_and_saveexec_b64 s[4:5], s[0:1]
	s_cbranch_execz .LBB0_534
	buffer_wbl2 sc1
	s_waitcnt vmcnt(0)
	v_readlane_b32 s6, v255, 60
	v_readlane_b32 s7, v255, 61
	v_readlane_b32 s8, v255, 63
	v_readlane_b32 s9, v255, 62
	s_add_u32 s6, s6, 0x7e00000
	s_addc_u32 s7, s7, 0
	s_and_b32 s10, s8, 7
	s_sub_i32 s11, s9, s10
	s_add_i32 s11, s11, 7
	s_lshr_b32 s11, s11, 3
	s_sub_i32 s11, 0x10001, s11
	s_cmp_lt_u32 s8, 8
	s_cselect_b32 s11, s11, 1
	s_lshl_b32 s8, s10, 8
	s_add_i32 s8, s8, 0x100
	v_mov_b32_e32 v2, s8
	v_mov_b32_e32 v3, s11
	global_atomic_add v3, v2, v3, s[6:7] sc0
	s_min_u32 s9, s9, 8
	s_sub_i32 s9, 0x10001, s9
	s_cmp_eq_u32 s10, 0
	s_cselect_b32 s9, s9, 1
	v_mov_b32_e32 v2, 0
	s_waitcnt vmcnt(0)
	v_readfirstlane_b32 s8, v3
	s_add_i32 s10, s8, s11
	s_xor_b32 s10, s10, s8
	s_lshr_b32 s10, s10, 16
	s_lshr_b32 s8, s8, 16
	s_cmp_eq_u32 s10, 0
	s_cbranch_scc1 .Lgb_poll_8
	v_mov_b32_e32 v3, s9
	global_atomic_add v2, v3, s[6:7]

.LBB0_545:
	s_cmp_eq_u32 s84, 3
	s_cselect_b64 s[4:5], -1, 0
	s_add_i32 s85, s85, 10
	s_cmp_lt_i32 s85, s99
	s_cselect_b64 s[6:7], -1, 0
	s_and_b64 s[4:5], s[4:5], s[6:7]
	s_and_b64 vcc, exec, s[4:5]
	s_cbranch_vccz .LBB0_394
	s_waitcnt vmcnt(0) lgkmcnt(0)
	s_barrier
	s_and_saveexec_b64 s[4:5], s[0:1]
	s_cbranch_execz .LBB0_393
	buffer_wbl2 sc1
	s_waitcnt vmcnt(0)
	v_readlane_b32 s6, v255, 60
	v_readlane_b32 s7, v255, 61
	v_readlane_b32 s8, v255, 63
	v_readlane_b32 s9, v255, 62
	s_add_u32 s6, s6, 0x7e00000
	s_addc_u32 s7, s7, 0
	s_and_b32 s10, s8, 7
	s_sub_i32 s11, s9, s10
	s_add_i32 s11, s11, 7
	s_lshr_b32 s11, s11, 3
	s_sub_i32 s11, 0x10001, s11
	s_cmp_lt_u32 s8, 8
	s_cselect_b32 s11, s11, 1
	s_lshl_b32 s8, s10, 8
	s_add_i32 s8, s8, 0x100
	v_mov_b32_e32 v2, s8
	v_mov_b32_e32 v3, s11
	global_atomic_add v3, v2, v3, s[6:7] sc0
	s_min_u32 s9, s9, 8
	s_sub_i32 s9, 0x10001, s9
	s_cmp_eq_u32 s10, 0
	s_cselect_b32 s9, s9, 1
	v_mov_b32_e32 v2, 0
	s_waitcnt vmcnt(0)
	v_readfirstlane_b32 s8, v3
	s_add_i32 s10, s8, s11
	s_xor_b32 s10, s10, s8
	s_lshr_b32 s10, s10, 16
	s_lshr_b32 s8, s8, 16
	s_cmp_eq_u32 s10, 0
	s_cbranch_scc1 .Lgb_poll_9
	v_mov_b32_e32 v3, s9
	global_atomic_add v2, v3, s[6:7]

.Lgb_done_9:
	buffer_inv sc1
	s_waitcnt vmcnt(0)
	s_branch .LBB0_393
